# closed-form next-unit index in P8 unit header (same row panel, column tile +4) replacing the division sequence
# baseline (speedup 1.0000x reference)
;     __host__ __device__ bool next(int i, Unit& u) const { const int L = i * G + c; if (L >= n) return false; u.pm = L; u.pn = L >> 2; return true; }
;     __host__ __device__ bool next(int i, Unit& u) const {
;         const long L = (long)i * G + c; if (L >= nwg) return false;
;         int wgid = (int)L; { const int q = nwg / NXCD, r = nwg % NXCD, xcd = wgid % NXCD, off = wgid / NXCD; wgid = (xcd < r ? xcd * (q + 1) : r * (q + 1) + (xcd - r) * q) + off; }
;         const int nig = WGM * nN, gid = wgid / nig, fm = gid * WGM, gsz = (nM - fm) < WGM ? (nM - fm) : WGM;
;         u.pm = fm + ((wgid % nig) % gsz); u.pn = (wgid % nig) / gsz; return true;
; template <class Epi, class Sched, bool ALIGN_EPI>
; __device__ __forceinline__ void gemm_phase(PG8_LAS unsigned char* lds, const Gemm g, const Sched& S, const Epi& E) {
;     ...
;         const bool has_next = S.next(ui + 1, nxt);
.LBB0_898:
	s_add_i32 s42, s42, 1
	s_mul_i32 s0, s42, s4
	s_mul_hi_u32 s1, s42, s33
	s_add_i32 s1, s1, s0
	s_mul_i32 s0, s42, s33
	s_add_u32 s22, s0, s74
	s_addc_u32 s23, s1, s36
	v_cmp_gt_i64_e32 vcc, s[22:23], v[144:145]
	v_cmp_lt_i64_e64 s[0:1], s[22:23], v[142:143]
	s_mov_b64 s[24:25], 0xf00
	s_cbranch_vccnz .LBB0_900
	s_add_i32 s18, s48, 4
	s_mov_b32 s20, s26
	s_mov_b64 s[24:25], 0
